# S5 GLU GEMM: 4-deep pipelined W stream with counted waits (was one load per vmcnt(0)); bias prefetched; no full drains in its epilogue
# speedup vs baseline: 1.0076x; 1.0076x over previous
.LBB0_1202:
	s_mov_b64 s[4:5], 0x300000
	v_lshl_add_u64 v[30:31], v[78:79], 0, s[4:5]
	s_mov_b64 s[4:5], 0x304000
	v_lshl_add_u64 v[32:33], v[78:79], 0, s[4:5]
	s_mov_b64 s[4:5], 0x308000
	v_lshl_add_u64 v[56:57], v[78:79], 0, s[4:5]
	s_mov_b64 s[4:5], 0x30c000
	v_lshl_add_u64 v[42:43], v[78:79], 0, s[4:5]
	global_load_dwordx4 v[126:129], v[30:31], off
	global_load_dwordx4 v[130:133], v[32:33], off
	global_load_dwordx4 v[134:137], v[56:57], off
	global_load_dwordx4 v[138:141], v[42:43], off
	global_load_dwordx4 v[142:145], v[30:31], off offset:64
	global_load_dwordx4 v[146:149], v[32:33], off offset:64
	global_load_dwordx4 v[150:153], v[56:57], off offset:64
	global_load_dwordx4 v[154:157], v[42:43], off offset:64
	global_load_dwordx4 v[158:161], v[30:31], off offset:128
	global_load_dwordx4 v[162:165], v[32:33], off offset:128
	global_load_dwordx4 v[166:169], v[56:57], off offset:128
	global_load_dwordx4 v[170:173], v[42:43], off offset:128
	global_load_dwordx4 v[174:177], v[30:31], off offset:192
	global_load_dwordx4 v[190:193], v[32:33], off offset:192
	global_load_dwordx4 v[194:197], v[56:57], off offset:192
	global_load_dwordx4 v[198:201], v[42:43], off offset:192
	global_load_dwordx4 v[202:205], v[76:77], off
	global_load_dwordx4 v[206:209], v[76:77], off offset:64
	global_load_dwordx4 v[210:213], v[76:77], off offset:128
	global_load_dwordx4 v[214:217], v[76:77], off offset:192
	ds_read_b128 v[38:41], v112
	ds_read_b128 v[44:47], v112 offset:16640
	ds_read_b128 v[48:51], v112 offset:64
	ds_read_b128 v[52:55], v112 offset:16704
	s_waitcnt vmcnt(16) lgkmcnt(2)
	v_mfma_f32_16x16x32_bf16 v[34:37], v[126:129], v[38:41], v[34:37]
	v_mfma_f32_16x16x32_bf16 v[26:29], v[126:129], v[44:47], v[26:29]
	v_mfma_f32_16x16x32_bf16 v[22:25], v[130:133], v[38:41], v[22:25]
	v_mfma_f32_16x16x32_bf16 v[18:21], v[130:133], v[44:47], v[18:21]
	v_mfma_f32_16x16x32_bf16 v[14:17], v[134:137], v[38:41], v[14:17]
	v_mfma_f32_16x16x32_bf16 v[10:13], v[134:137], v[44:47], v[10:13]
	v_mfma_f32_16x16x32_bf16 v[6:9], v[138:141], v[38:41], v[6:9]
	v_mfma_f32_16x16x32_bf16 v[2:5], v[138:141], v[44:47], v[2:5]
	global_load_dwordx4 v[126:129], v[30:31], off offset:256
	global_load_dwordx4 v[130:133], v[32:33], off offset:256
	global_load_dwordx4 v[134:137], v[56:57], off offset:256
	global_load_dwordx4 v[138:141], v[42:43], off offset:256
	ds_read_b128 v[38:41], v112 offset:128
	ds_read_b128 v[44:47], v112 offset:16768
	s_waitcnt vmcnt(16) lgkmcnt(2)
	v_mfma_f32_16x16x32_bf16 v[34:37], v[142:145], v[48:51], v[34:37]
	v_mfma_f32_16x16x32_bf16 v[26:29], v[142:145], v[52:55], v[26:29]
	v_mfma_f32_16x16x32_bf16 v[22:25], v[146:149], v[48:51], v[22:25]
	v_mfma_f32_16x16x32_bf16 v[18:21], v[146:149], v[52:55], v[18:21]
	v_mfma_f32_16x16x32_bf16 v[14:17], v[150:153], v[48:51], v[14:17]
	v_mfma_f32_16x16x32_bf16 v[10:13], v[150:153], v[52:55], v[10:13]
	v_mfma_f32_16x16x32_bf16 v[6:9], v[154:157], v[48:51], v[6:9]
	v_mfma_f32_16x16x32_bf16 v[2:5], v[154:157], v[52:55], v[2:5]
	global_load_dwordx4 v[142:145], v[30:31], off offset:320
	global_load_dwordx4 v[146:149], v[32:33], off offset:320
	global_load_dwordx4 v[150:153], v[56:57], off offset:320
	global_load_dwordx4 v[154:157], v[42:43], off offset:320
	ds_read_b128 v[48:51], v112 offset:192
	ds_read_b128 v[52:55], v112 offset:16832
	s_waitcnt vmcnt(16) lgkmcnt(2)
	v_mfma_f32_16x16x32_bf16 v[34:37], v[158:161], v[38:41], v[34:37]
	v_mfma_f32_16x16x32_bf16 v[26:29], v[158:161], v[44:47], v[26:29]
	v_mfma_f32_16x16x32_bf16 v[22:25], v[162:165], v[38:41], v[22:25]
	v_mfma_f32_16x16x32_bf16 v[18:21], v[162:165], v[44:47], v[18:21]
	v_mfma_f32_16x16x32_bf16 v[14:17], v[166:169], v[38:41], v[14:17]
	v_mfma_f32_16x16x32_bf16 v[10:13], v[166:169], v[44:47], v[10:13]
	v_mfma_f32_16x16x32_bf16 v[6:9], v[170:173], v[38:41], v[6:9]
	v_mfma_f32_16x16x32_bf16 v[2:5], v[170:173], v[44:47], v[2:5]
	global_load_dwordx4 v[158:161], v[30:31], off offset:384
	global_load_dwordx4 v[162:165], v[32:33], off offset:384
	global_load_dwordx4 v[166:169], v[56:57], off offset:384
	global_load_dwordx4 v[170:173], v[42:43], off offset:384
	ds_read_b128 v[38:41], v112 offset:256
	ds_read_b128 v[44:47], v112 offset:16896
	s_waitcnt vmcnt(16) lgkmcnt(2)
	v_mfma_f32_16x16x32_bf16 v[34:37], v[174:177], v[48:51], v[34:37]
	v_mfma_f32_16x16x32_bf16 v[26:29], v[174:177], v[52:55], v[26:29]
	v_mfma_f32_16x16x32_bf16 v[22:25], v[190:193], v[48:51], v[22:25]
	v_mfma_f32_16x16x32_bf16 v[18:21], v[190:193], v[52:55], v[18:21]
	v_mfma_f32_16x16x32_bf16 v[14:17], v[194:197], v[48:51], v[14:17]
	v_mfma_f32_16x16x32_bf16 v[10:13], v[194:197], v[52:55], v[10:13]
	v_mfma_f32_16x16x32_bf16 v[6:9], v[198:201], v[48:51], v[6:9]
	v_mfma_f32_16x16x32_bf16 v[2:5], v[198:201], v[52:55], v[2:5]
	global_load_dwordx4 v[174:177], v[30:31], off offset:448
	global_load_dwordx4 v[190:193], v[32:33], off offset:448
	global_load_dwordx4 v[194:197], v[56:57], off offset:448
	global_load_dwordx4 v[198:201], v[42:43], off offset:448
	ds_read_b128 v[48:51], v112 offset:320
	ds_read_b128 v[52:55], v112 offset:16960
	s_waitcnt vmcnt(12) lgkmcnt(2)
	v_mfma_f32_16x16x32_bf16 v[34:37], v[126:129], v[38:41], v[34:37]
	v_mfma_f32_16x16x32_bf16 v[26:29], v[126:129], v[44:47], v[26:29]
	v_mfma_f32_16x16x32_bf16 v[22:25], v[130:133], v[38:41], v[22:25]
	v_mfma_f32_16x16x32_bf16 v[18:21], v[130:133], v[44:47], v[18:21]
	v_mfma_f32_16x16x32_bf16 v[14:17], v[134:137], v[38:41], v[14:17]
	v_mfma_f32_16x16x32_bf16 v[10:13], v[134:137], v[44:47], v[10:13]
	v_mfma_f32_16x16x32_bf16 v[6:9], v[138:141], v[38:41], v[6:9]
	v_mfma_f32_16x16x32_bf16 v[2:5], v[138:141], v[44:47], v[2:5]
	global_load_dwordx4 v[126:129], v[30:31], off offset:512
	global_load_dwordx4 v[130:133], v[32:33], off offset:512
	global_load_dwordx4 v[134:137], v[56:57], off offset:512
	global_load_dwordx4 v[138:141], v[42:43], off offset:512
	ds_read_b128 v[38:41], v112 offset:384
	ds_read_b128 v[44:47], v112 offset:17024
	s_waitcnt vmcnt(12) lgkmcnt(2)
	v_mfma_f32_16x16x32_bf16 v[34:37], v[142:145], v[48:51], v[34:37]
	v_mfma_f32_16x16x32_bf16 v[26:29], v[142:145], v[52:55], v[26:29]
	v_mfma_f32_16x16x32_bf16 v[22:25], v[146:149], v[48:51], v[22:25]
	v_mfma_f32_16x16x32_bf16 v[18:21], v[146:149], v[52:55], v[18:21]
	v_mfma_f32_16x16x32_bf16 v[14:17], v[150:153], v[48:51], v[14:17]
	v_mfma_f32_16x16x32_bf16 v[10:13], v[150:153], v[52:55], v[10:13]
	v_mfma_f32_16x16x32_bf16 v[6:9], v[154:157], v[48:51], v[6:9]
	v_mfma_f32_16x16x32_bf16 v[2:5], v[154:157], v[52:55], v[2:5]
	global_load_dwordx4 v[142:145], v[30:31], off offset:576
	global_load_dwordx4 v[146:149], v[32:33], off offset:576
	global_load_dwordx4 v[150:153], v[56:57], off offset:576
	global_load_dwordx4 v[154:157], v[42:43], off offset:576
	ds_read_b128 v[48:51], v112 offset:448
	ds_read_b128 v[52:55], v112 offset:17088
	s_waitcnt vmcnt(12) lgkmcnt(2)
	v_mfma_f32_16x16x32_bf16 v[34:37], v[158:161], v[38:41], v[34:37]
	v_mfma_f32_16x16x32_bf16 v[26:29], v[158:161], v[44:47], v[26:29]
	v_mfma_f32_16x16x32_bf16 v[22:25], v[162:165], v[38:41], v[22:25]
	v_mfma_f32_16x16x32_bf16 v[18:21], v[162:165], v[44:47], v[18:21]
	v_mfma_f32_16x16x32_bf16 v[14:17], v[166:169], v[38:41], v[14:17]
	v_mfma_f32_16x16x32_bf16 v[10:13], v[166:169], v[44:47], v[10:13]
	v_mfma_f32_16x16x32_bf16 v[6:9], v[170:173], v[38:41], v[6:9]
	v_mfma_f32_16x16x32_bf16 v[2:5], v[170:173], v[44:47], v[2:5]
	global_load_dwordx4 v[158:161], v[30:31], off offset:640
	global_load_dwordx4 v[162:165], v[32:33], off offset:640
	global_load_dwordx4 v[166:169], v[56:57], off offset:640
	global_load_dwordx4 v[170:173], v[42:43], off offset:640
	ds_read_b128 v[38:41], v112 offset:512
	ds_read_b128 v[44:47], v112 offset:17152
	s_waitcnt vmcnt(12) lgkmcnt(2)
	v_mfma_f32_16x16x32_bf16 v[34:37], v[174:177], v[48:51], v[34:37]
	v_mfma_f32_16x16x32_bf16 v[26:29], v[174:177], v[52:55], v[26:29]
	v_mfma_f32_16x16x32_bf16 v[22:25], v[190:193], v[48:51], v[22:25]
	v_mfma_f32_16x16x32_bf16 v[18:21], v[190:193], v[52:55], v[18:21]
	v_mfma_f32_16x16x32_bf16 v[14:17], v[194:197], v[48:51], v[14:17]
	v_mfma_f32_16x16x32_bf16 v[10:13], v[194:197], v[52:55], v[10:13]
	v_mfma_f32_16x16x32_bf16 v[6:9], v[198:201], v[48:51], v[6:9]
	v_mfma_f32_16x16x32_bf16 v[2:5], v[198:201], v[52:55], v[2:5]
	global_load_dwordx4 v[174:177], v[30:31], off offset:704
	global_load_dwordx4 v[190:193], v[32:33], off offset:704
	global_load_dwordx4 v[194:197], v[56:57], off offset:704
	global_load_dwordx4 v[198:201], v[42:43], off offset:704
	ds_read_b128 v[48:51], v112 offset:576
	ds_read_b128 v[52:55], v112 offset:17216
	s_waitcnt vmcnt(12) lgkmcnt(2)
	v_mfma_f32_16x16x32_bf16 v[34:37], v[126:129], v[38:41], v[34:37]
	v_mfma_f32_16x16x32_bf16 v[26:29], v[126:129], v[44:47], v[26:29]
	v_mfma_f32_16x16x32_bf16 v[22:25], v[130:133], v[38:41], v[22:25]
	v_mfma_f32_16x16x32_bf16 v[18:21], v[130:133], v[44:47], v[18:21]
	v_mfma_f32_16x16x32_bf16 v[14:17], v[134:137], v[38:41], v[14:17]
	v_mfma_f32_16x16x32_bf16 v[10:13], v[134:137], v[44:47], v[10:13]
	v_mfma_f32_16x16x32_bf16 v[6:9], v[138:141], v[38:41], v[6:9]
	v_mfma_f32_16x16x32_bf16 v[2:5], v[138:141], v[44:47], v[2:5]
	global_load_dwordx4 v[126:129], v[30:31], off offset:768
	global_load_dwordx4 v[130:133], v[32:33], off offset:768
	global_load_dwordx4 v[134:137], v[56:57], off offset:768
	global_load_dwordx4 v[138:141], v[42:43], off offset:768
	ds_read_b128 v[38:41], v112 offset:640
	ds_read_b128 v[44:47], v112 offset:17280
	s_waitcnt vmcnt(12) lgkmcnt(2)
	v_mfma_f32_16x16x32_bf16 v[34:37], v[142:145], v[48:51], v[34:37]
	v_mfma_f32_16x16x32_bf16 v[26:29], v[142:145], v[52:55], v[26:29]
	v_mfma_f32_16x16x32_bf16 v[22:25], v[146:149], v[48:51], v[22:25]
	v_mfma_f32_16x16x32_bf16 v[18:21], v[146:149], v[52:55], v[18:21]
	v_mfma_f32_16x16x32_bf16 v[14:17], v[150:153], v[48:51], v[14:17]
	v_mfma_f32_16x16x32_bf16 v[10:13], v[150:153], v[52:55], v[10:13]
	v_mfma_f32_16x16x32_bf16 v[6:9], v[154:157], v[48:51], v[6:9]
	v_mfma_f32_16x16x32_bf16 v[2:5], v[154:157], v[52:55], v[2:5]
	global_load_dwordx4 v[142:145], v[30:31], off offset:832
	global_load_dwordx4 v[146:149], v[32:33], off offset:832
	global_load_dwordx4 v[150:153], v[56:57], off offset:832
	global_load_dwordx4 v[154:157], v[42:43], off offset:832
	ds_read_b128 v[48:51], v112 offset:704
	ds_read_b128 v[52:55], v112 offset:17344
	s_waitcnt vmcnt(12) lgkmcnt(2)
	v_mfma_f32_16x16x32_bf16 v[34:37], v[158:161], v[38:41], v[34:37]
	v_mfma_f32_16x16x32_bf16 v[26:29], v[158:161], v[44:47], v[26:29]
	v_mfma_f32_16x16x32_bf16 v[22:25], v[162:165], v[38:41], v[22:25]
	v_mfma_f32_16x16x32_bf16 v[18:21], v[162:165], v[44:47], v[18:21]
	v_mfma_f32_16x16x32_bf16 v[14:17], v[166:169], v[38:41], v[14:17]
	v_mfma_f32_16x16x32_bf16 v[10:13], v[166:169], v[44:47], v[10:13]
	v_mfma_f32_16x16x32_bf16 v[6:9], v[170:173], v[38:41], v[6:9]
	v_mfma_f32_16x16x32_bf16 v[2:5], v[170:173], v[44:47], v[2:5]
	global_load_dwordx4 v[158:161], v[30:31], off offset:896
	global_load_dwordx4 v[162:165], v[32:33], off offset:896
	global_load_dwordx4 v[166:169], v[56:57], off offset:896
	global_load_dwordx4 v[170:173], v[42:43], off offset:896
	ds_read_b128 v[38:41], v112 offset:768
	ds_read_b128 v[44:47], v112 offset:17408
	s_waitcnt vmcnt(12) lgkmcnt(2)
	v_mfma_f32_16x16x32_bf16 v[34:37], v[174:177], v[48:51], v[34:37]
	v_mfma_f32_16x16x32_bf16 v[26:29], v[174:177], v[52:55], v[26:29]
	v_mfma_f32_16x16x32_bf16 v[22:25], v[190:193], v[48:51], v[22:25]
	v_mfma_f32_16x16x32_bf16 v[18:21], v[190:193], v[52:55], v[18:21]
	v_mfma_f32_16x16x32_bf16 v[14:17], v[194:197], v[48:51], v[14:17]
	v_mfma_f32_16x16x32_bf16 v[10:13], v[194:197], v[52:55], v[10:13]
	v_mfma_f32_16x16x32_bf16 v[6:9], v[198:201], v[48:51], v[6:9]
	v_mfma_f32_16x16x32_bf16 v[2:5], v[198:201], v[52:55], v[2:5]
	global_load_dwordx4 v[174:177], v[30:31], off offset:960
	global_load_dwordx4 v[190:193], v[32:33], off offset:960
	global_load_dwordx4 v[194:197], v[56:57], off offset:960
	global_load_dwordx4 v[198:201], v[42:43], off offset:960
	ds_read_b128 v[48:51], v112 offset:832
	ds_read_b128 v[52:55], v112 offset:17472
	s_waitcnt vmcnt(12) lgkmcnt(2)
	v_mfma_f32_16x16x32_bf16 v[34:37], v[126:129], v[38:41], v[34:37]
	v_mfma_f32_16x16x32_bf16 v[26:29], v[126:129], v[44:47], v[26:29]
	v_mfma_f32_16x16x32_bf16 v[22:25], v[130:133], v[38:41], v[22:25]
	v_mfma_f32_16x16x32_bf16 v[18:21], v[130:133], v[44:47], v[18:21]
	v_mfma_f32_16x16x32_bf16 v[14:17], v[134:137], v[38:41], v[14:17]
	v_mfma_f32_16x16x32_bf16 v[10:13], v[134:137], v[44:47], v[10:13]
	v_mfma_f32_16x16x32_bf16 v[6:9], v[138:141], v[38:41], v[6:9]
	v_mfma_f32_16x16x32_bf16 v[2:5], v[138:141], v[44:47], v[2:5]
	ds_read_b128 v[38:41], v112 offset:896
	ds_read_b128 v[44:47], v112 offset:17536
	s_waitcnt vmcnt(8) lgkmcnt(2)
	v_mfma_f32_16x16x32_bf16 v[34:37], v[142:145], v[48:51], v[34:37]
	v_mfma_f32_16x16x32_bf16 v[26:29], v[142:145], v[52:55], v[26:29]
	v_mfma_f32_16x16x32_bf16 v[22:25], v[146:149], v[48:51], v[22:25]
	v_mfma_f32_16x16x32_bf16 v[18:21], v[146:149], v[52:55], v[18:21]
	v_mfma_f32_16x16x32_bf16 v[14:17], v[150:153], v[48:51], v[14:17]
	v_mfma_f32_16x16x32_bf16 v[10:13], v[150:153], v[52:55], v[10:13]
	v_mfma_f32_16x16x32_bf16 v[6:9], v[154:157], v[48:51], v[6:9]
	v_mfma_f32_16x16x32_bf16 v[2:5], v[154:157], v[52:55], v[2:5]
	ds_read_b128 v[48:51], v112 offset:960
	ds_read_b128 v[52:55], v112 offset:17600
	s_waitcnt vmcnt(4) lgkmcnt(2)
	v_mfma_f32_16x16x32_bf16 v[34:37], v[158:161], v[38:41], v[34:37]
	v_mfma_f32_16x16x32_bf16 v[26:29], v[158:161], v[44:47], v[26:29]
	v_mfma_f32_16x16x32_bf16 v[22:25], v[162:165], v[38:41], v[22:25]
	v_mfma_f32_16x16x32_bf16 v[18:21], v[162:165], v[44:47], v[18:21]
	v_mfma_f32_16x16x32_bf16 v[14:17], v[166:169], v[38:41], v[14:17]
	v_mfma_f32_16x16x32_bf16 v[10:13], v[166:169], v[44:47], v[10:13]
	v_mfma_f32_16x16x32_bf16 v[6:9], v[170:173], v[38:41], v[6:9]
	v_mfma_f32_16x16x32_bf16 v[2:5], v[170:173], v[44:47], v[2:5]
	s_waitcnt vmcnt(0) lgkmcnt(0)
	v_mfma_f32_16x16x32_bf16 v[34:37], v[174:177], v[48:51], v[34:37]
	v_mfma_f32_16x16x32_bf16 v[26:29], v[174:177], v[52:55], v[26:29]
	v_mfma_f32_16x16x32_bf16 v[22:25], v[190:193], v[48:51], v[22:25]
	v_mfma_f32_16x16x32_bf16 v[18:21], v[190:193], v[52:55], v[18:21]
	v_mfma_f32_16x16x32_bf16 v[14:17], v[194:197], v[48:51], v[14:17]
	v_mfma_f32_16x16x32_bf16 v[10:13], v[194:197], v[52:55], v[10:13]
	v_mfma_f32_16x16x32_bf16 v[6:9], v[198:201], v[48:51], v[6:9]
	v_mfma_f32_16x16x32_bf16 v[2:5], v[198:201], v[52:55], v[2:5]
	s_mov_b64 s[4:5], 0x400
	v_mov_b32_e32 v30, v202
	v_mov_b32_e32 v31, v203
	v_mov_b32_e32 v32, v204
	v_mov_b32_e32 v33, v205
	ds_read_b64 v[38:39], v113
	v_ashrrev_i32_e32 v93, 31, v92
	s_mov_b64 s[6:7], 0x23c00400
	v_readlane_b32 s48, v255, 0
	v_readlane_b32 s54, v255, 6
	s_add_i32 s11, s11, s54
	s_cmpk_gt_i32 s11, 0xff
	v_readlane_b32 s49, v255, 1
	v_readlane_b32 s50, v255, 2
	v_readlane_b32 s51, v255, 3
	v_readlane_b32 s52, v255, 4
	v_readlane_b32 s53, v255, 5
	v_readlane_b32 s55, v255, 7
	v_pk_add_f32 v[34:35], v[34:35], v[30:31]
	v_pk_add_f32 v[36:37], v[36:37], v[32:33]
	v_mul_f32_e32 v35, 0xbfb8aa3b, v35
	v_mul_f32_e32 v34, 0xbfb8aa3b, v34
	v_exp_f32_e32 v40, v35
	v_mul_f32_e32 v35, 0xbfb8aa3b, v36
	v_exp_f32_e32 v34, v34
	v_exp_f32_e32 v35, v35
	v_mul_f32_e32 v36, 0xbfb8aa3b, v37
	v_exp_f32_e32 v41, v36
	s_waitcnt lgkmcnt(0)
	v_lshlrev_b32_e32 v37, 16, v39
	v_pk_add_f32 v[34:35], v[34:35], 1.0 op_sel_hi:[1,0]
	v_lshlrev_b32_e32 v36, 16, v38
	v_and_b32_e32 v39, 0xffff0000, v39
	v_and_b32_e32 v38, 0xffff0000, v38
	v_pk_add_f32 v[26:27], v[26:27], v[30:31]
	v_rcp_f32_e32 v35, v35
	s_nop 0
	v_mul_f32_e32 v26, 0xbfb8aa3b, v26
	v_pk_add_f32 v[32:33], v[28:29], v[32:33]
	v_rcp_f32_e32 v34, v34
	s_nop 0
	v_pk_mul_f32 v[34:35], v[34:35], v[36:37]
	v_pk_add_f32 v[36:37], v[40:41], 1.0 op_sel_hi:[1,0]
	s_nop 0
	s_nop 0
	v_rcp_f32_e32 v37, v37
	s_nop 0
	s_nop 0
	v_rcp_f32_e32 v36, v36
	s_nop 0
	v_pk_mul_f32 v[36:37], v[36:37], v[38:39]
	v_and_b32_sdwa v38, v35, v225 dst_sel:DWORD dst_unused:UNUSED_PAD src0_sel:WORD_1 src1_sel:DWORD
	v_and_b32_sdwa v39, v34, v225 dst_sel:DWORD dst_unused:UNUSED_PAD src0_sel:WORD_1 src1_sel:DWORD
	v_add3_u32 v34, v34, v39, s23
	v_add3_u32 v35, v35, v38, s23
	v_and_b32_sdwa v38, v37, v225 dst_sel:DWORD dst_unused:UNUSED_PAD src0_sel:WORD_1 src1_sel:DWORD
	v_and_b32_sdwa v39, v36, v225 dst_sel:DWORD dst_unused:UNUSED_PAD src0_sel:WORD_1 src1_sel:DWORD
	v_add3_u32 v37, v37, v38, s23
	v_add3_u32 v36, v36, v39, s23
	v_and_b32_e32 v37, 0xffff0000, v37
	v_and_b32_e32 v36, 0xffff0000, v36
	v_or_b32_sdwa v37, v37, v35 dst_sel:DWORD dst_unused:UNUSED_PAD src0_sel:DWORD src1_sel:WORD_1
	v_or_b32_sdwa v36, v36, v34 dst_sel:DWORD dst_unused:UNUSED_PAD src0_sel:DWORD src1_sel:WORD_1
	v_lshlrev_b64 v[34:35], 12, v[92:93]
	v_lshl_add_u64 v[34:35], s[0:1], 0, v[34:35]
	v_lshl_add_u64 v[34:35], v[34:35], 0, s[6:7]
	v_lshl_add_u64 v[38:39], v[34:35], 0, v[84:85]
	global_store_dwordx2 v[38:39], v[36:37], off
	v_exp_f32_e32 v38, v26
	v_mul_f32_e32 v26, 0xbfb8aa3b, v27
	v_exp_f32_e32 v28, v26
	v_mul_f32_e32 v26, 0xbfb8aa3b, v32
	ds_read_b64 v[36:37], v113 offset:16640
	v_exp_f32_e32 v39, v26
	v_mul_f32_e32 v26, 0xbfb8aa3b, v33
	v_exp_f32_e32 v29, v26
	v_pk_add_f32 v[32:33], v[38:39], 1.0 op_sel_hi:[1,0]
	s_waitcnt lgkmcnt(0)
	v_lshlrev_b32_e32 v30, 16, v36
	v_and_b32_e32 v26, 0xffff0000, v36
	v_lshlrev_b32_e32 v31, 16, v37
	v_and_b32_e32 v27, 0xffff0000, v37
	v_pk_add_f32 v[28:29], v[28:29], 1.0 op_sel_hi:[1,0]
	v_rcp_f32_e32 v33, v33
	s_nop 0
	s_nop 0
	v_rcp_f32_e32 v32, v32
	s_nop 0
	v_pk_mul_f32 v[30:31], v[32:33], v[30:31]
	s_nop 0
	v_rcp_f32_e32 v29, v29
	s_nop 0
	s_nop 0
	v_rcp_f32_e32 v28, v28
	s_nop 0
	v_pk_mul_f32 v[26:27], v[28:29], v[26:27]
	v_and_b32_sdwa v29, v30, v225 dst_sel:DWORD dst_unused:UNUSED_PAD src0_sel:WORD_1 src1_sel:DWORD
	v_and_b32_sdwa v28, v31, v225 dst_sel:DWORD dst_unused:UNUSED_PAD src0_sel:WORD_1 src1_sel:DWORD
	v_add3_u32 v29, v30, v29, s23
	v_and_b32_sdwa v30, v27, v225 dst_sel:DWORD dst_unused:UNUSED_PAD src0_sel:WORD_1 src1_sel:DWORD
	v_add3_u32 v28, v31, v28, s23
	v_and_b32_sdwa v31, v26, v225 dst_sel:DWORD dst_unused:UNUSED_PAD src0_sel:WORD_1 src1_sel:DWORD
	v_add3_u32 v27, v27, v30, s23
	v_add3_u32 v26, v26, v31, s23
	v_and_b32_e32 v27, 0xffff0000, v27
	v_and_b32_e32 v26, 0xffff0000, v26
	v_or_b32_sdwa v27, v27, v28 dst_sel:DWORD dst_unused:UNUSED_PAD src0_sel:DWORD src1_sel:WORD_1
	v_or_b32_e32 v28, s8, v102
	v_or_b32_sdwa v26, v26, v29 dst_sel:DWORD dst_unused:UNUSED_PAD src0_sel:DWORD src1_sel:WORD_1
	v_ashrrev_i32_e32 v29, 31, v28
	v_lshlrev_b64 v[28:29], 12, v[28:29]
	v_lshl_add_u64 v[28:29], s[0:1], 0, v[28:29]
	v_lshl_add_u64 v[30:31], v[28:29], 0, s[6:7]
	v_lshl_add_u64 v[28:29], v[30:31], 0, v[84:85]
	global_store_dwordx2 v[28:29], v[26:27], off
	v_mov_b32_e32 v26, v206
	v_mov_b32_e32 v27, v207
	v_mov_b32_e32 v28, v208
	v_mov_b32_e32 v29, v209
	ds_read_b64 v[32:33], v106
	v_pk_add_f32 v[22:23], v[22:23], v[26:27]
	v_pk_add_f32 v[24:25], v[24:25], v[28:29]
	v_mul_f32_e32 v23, 0xbfb8aa3b, v23
	v_mul_f32_e32 v22, 0xbfb8aa3b, v22
	v_exp_f32_e32 v36, v23
	v_mul_f32_e32 v23, 0xbfb8aa3b, v24
	v_exp_f32_e32 v22, v22
	v_exp_f32_e32 v23, v23
	v_mul_f32_e32 v24, 0xbfb8aa3b, v25
	v_exp_f32_e32 v37, v24
	s_waitcnt lgkmcnt(0)
	v_lshlrev_b32_e32 v25, 16, v33
	v_pk_add_f32 v[22:23], v[22:23], 1.0 op_sel_hi:[1,0]
	v_lshlrev_b32_e32 v24, 16, v32
	v_and_b32_e32 v33, 0xffff0000, v33
	v_and_b32_e32 v32, 0xffff0000, v32
	v_pk_add_f32 v[18:19], v[18:19], v[26:27]
	v_rcp_f32_e32 v23, v23
	s_nop 0
	v_pk_add_f32 v[20:21], v[20:21], v[28:29]
	v_mul_f32_e32 v19, 0xbfb8aa3b, v19
	v_mul_f32_e32 v18, 0xbfb8aa3b, v18
	v_rcp_f32_e32 v22, v22
	s_nop 0
	v_pk_mul_f32 v[22:23], v[22:23], v[24:25]
	v_pk_add_f32 v[24:25], v[36:37], 1.0 op_sel_hi:[1,0]
	v_exp_f32_e32 v18, v18
	s_nop 0
	v_rcp_f32_e32 v25, v25
	s_nop 0
	s_nop 0
	v_rcp_f32_e32 v24, v24
	s_nop 0
	v_pk_mul_f32 v[24:25], v[24:25], v[32:33]
	v_and_b32_sdwa v32, v23, v225 dst_sel:DWORD dst_unused:UNUSED_PAD src0_sel:WORD_1 src1_sel:DWORD
	v_and_b32_sdwa v33, v22, v225 dst_sel:DWORD dst_unused:UNUSED_PAD src0_sel:WORD_1 src1_sel:DWORD
	v_add3_u32 v22, v22, v33, s23
	v_add3_u32 v23, v23, v32, s23
	v_and_b32_sdwa v32, v25, v225 dst_sel:DWORD dst_unused:UNUSED_PAD src0_sel:WORD_1 src1_sel:DWORD
	v_and_b32_sdwa v33, v24, v225 dst_sel:DWORD dst_unused:UNUSED_PAD src0_sel:WORD_1 src1_sel:DWORD
	v_add3_u32 v25, v25, v32, s23
	v_add3_u32 v24, v24, v33, s23
	v_and_b32_e32 v25, 0xffff0000, v25
	v_and_b32_e32 v24, 0xffff0000, v24
	v_or_b32_sdwa v23, v25, v23 dst_sel:DWORD dst_unused:UNUSED_PAD src0_sel:DWORD src1_sel:WORD_1
	v_or_b32_sdwa v22, v24, v22 dst_sel:DWORD dst_unused:UNUSED_PAD src0_sel:DWORD src1_sel:WORD_1
	v_lshl_add_u64 v[24:25], v[34:35], 0, v[86:87]
	global_store_dwordx2 v[24:25], v[22:23], off
	v_exp_f32_e32 v24, v19
	v_mul_f32_e32 v19, 0xbfb8aa3b, v20
	v_exp_f32_e32 v19, v19
	ds_read_b64 v[22:23], v107
	v_mul_f32_e32 v20, 0xbfb8aa3b, v21
	v_exp_f32_e32 v25, v20
	v_pk_add_f32 v[18:19], v[18:19], 1.0 op_sel_hi:[1,0]
	s_waitcnt lgkmcnt(0)
	v_lshlrev_b32_e32 v21, 16, v23
	v_lshlrev_b32_e32 v20, 16, v22
	v_and_b32_e32 v23, 0xffff0000, v23
	v_and_b32_e32 v22, 0xffff0000, v22
	v_rcp_f32_e32 v19, v19
	s_nop 0
	s_nop 0
	v_rcp_f32_e32 v18, v18
	s_nop 0
	v_pk_mul_f32 v[18:19], v[18:19], v[20:21]
	v_pk_add_f32 v[20:21], v[24:25], 1.0 op_sel_hi:[1,0]
	s_nop 0
	s_nop 0
	v_rcp_f32_e32 v21, v21
	s_nop 0
	s_nop 0
	v_rcp_f32_e32 v20, v20
	s_nop 0
	v_pk_mul_f32 v[20:21], v[20:21], v[22:23]
	v_and_b32_sdwa v22, v19, v225 dst_sel:DWORD dst_unused:UNUSED_PAD src0_sel:WORD_1 src1_sel:DWORD
	v_and_b32_sdwa v23, v18, v225 dst_sel:DWORD dst_unused:UNUSED_PAD src0_sel:WORD_1 src1_sel:DWORD
	v_add3_u32 v18, v18, v23, s23
	v_add3_u32 v19, v19, v22, s23
	v_and_b32_sdwa v22, v21, v225 dst_sel:DWORD dst_unused:UNUSED_PAD src0_sel:WORD_1 src1_sel:DWORD
	v_and_b32_sdwa v23, v20, v225 dst_sel:DWORD dst_unused:UNUSED_PAD src0_sel:WORD_1 src1_sel:DWORD
	v_add3_u32 v21, v21, v22, s23
	v_add3_u32 v20, v20, v23, s23
	v_and_b32_e32 v21, 0xffff0000, v21
	v_and_b32_e32 v20, 0xffff0000, v20
	v_or_b32_sdwa v19, v21, v19 dst_sel:DWORD dst_unused:UNUSED_PAD src0_sel:DWORD src1_sel:WORD_1
	v_or_b32_sdwa v18, v20, v18 dst_sel:DWORD dst_unused:UNUSED_PAD src0_sel:DWORD src1_sel:WORD_1
	v_lshl_add_u64 v[20:21], v[30:31], 0, v[86:87]
	global_store_dwordx2 v[20:21], v[18:19], off
	v_mov_b32_e32 v18, v210
	v_mov_b32_e32 v19, v211
	v_mov_b32_e32 v20, v212
	v_mov_b32_e32 v21, v213
	ds_read_b64 v[22:23], v108
	v_pk_add_f32 v[14:15], v[14:15], v[18:19]
	v_pk_add_f32 v[16:17], v[16:17], v[20:21]
	v_mul_f32_e32 v15, 0xbfb8aa3b, v15
	v_mul_f32_e32 v14, 0xbfb8aa3b, v14
	v_exp_f32_e32 v24, v15
	v_mul_f32_e32 v15, 0xbfb8aa3b, v16
	v_exp_f32_e32 v14, v14
	v_exp_f32_e32 v15, v15
	v_mul_f32_e32 v16, 0xbfb8aa3b, v17
	v_exp_f32_e32 v25, v16
	s_waitcnt lgkmcnt(0)
	v_lshlrev_b32_e32 v17, 16, v23
	v_pk_add_f32 v[14:15], v[14:15], 1.0 op_sel_hi:[1,0]
	v_lshlrev_b32_e32 v16, 16, v22
	v_and_b32_e32 v23, 0xffff0000, v23
	v_and_b32_e32 v22, 0xffff0000, v22
	v_pk_add_f32 v[10:11], v[10:11], v[18:19]
	v_rcp_f32_e32 v15, v15
	s_nop 0
	v_pk_add_f32 v[12:13], v[12:13], v[20:21]
	v_mul_f32_e32 v11, 0xbfb8aa3b, v11
	v_mul_f32_e32 v10, 0xbfb8aa3b, v10
	v_rcp_f32_e32 v14, v14
	s_nop 0
	v_pk_mul_f32 v[14:15], v[14:15], v[16:17]
	v_pk_add_f32 v[16:17], v[24:25], 1.0 op_sel_hi:[1,0]
	v_exp_f32_e32 v10, v10
	s_nop 0
	v_rcp_f32_e32 v17, v17
	s_nop 0
	s_nop 0
	v_rcp_f32_e32 v16, v16
	s_nop 0
	v_pk_mul_f32 v[16:17], v[16:17], v[22:23]
	v_and_b32_sdwa v22, v15, v225 dst_sel:DWORD dst_unused:UNUSED_PAD src0_sel:WORD_1 src1_sel:DWORD
	v_and_b32_sdwa v23, v14, v225 dst_sel:DWORD dst_unused:UNUSED_PAD src0_sel:WORD_1 src1_sel:DWORD
	v_add3_u32 v14, v14, v23, s23
	v_add3_u32 v15, v15, v22, s23
	v_and_b32_sdwa v22, v17, v225 dst_sel:DWORD dst_unused:UNUSED_PAD src0_sel:WORD_1 src1_sel:DWORD
	v_and_b32_sdwa v23, v16, v225 dst_sel:DWORD dst_unused:UNUSED_PAD src0_sel:WORD_1 src1_sel:DWORD
	v_add3_u32 v17, v17, v22, s23
	v_add3_u32 v16, v16, v23, s23
	v_and_b32_e32 v17, 0xffff0000, v17
	v_and_b32_e32 v16, 0xffff0000, v16
	v_or_b32_sdwa v15, v17, v15 dst_sel:DWORD dst_unused:UNUSED_PAD src0_sel:DWORD src1_sel:WORD_1
	v_or_b32_sdwa v14, v16, v14 dst_sel:DWORD dst_unused:UNUSED_PAD src0_sel:DWORD src1_sel:WORD_1
	v_lshl_add_u64 v[16:17], v[34:35], 0, v[88:89]
	global_store_dwordx2 v[16:17], v[14:15], off
	v_exp_f32_e32 v16, v11
	v_mul_f32_e32 v11, 0xbfb8aa3b, v12
	v_exp_f32_e32 v11, v11
	ds_read_b64 v[14:15], v109
	v_mul_f32_e32 v12, 0xbfb8aa3b, v13
	v_exp_f32_e32 v17, v12
	v_pk_add_f32 v[10:11], v[10:11], 1.0 op_sel_hi:[1,0]
	s_waitcnt lgkmcnt(0)
	v_lshlrev_b32_e32 v13, 16, v15
	v_lshlrev_b32_e32 v12, 16, v14
	v_and_b32_e32 v15, 0xffff0000, v15
	v_and_b32_e32 v14, 0xffff0000, v14
	v_rcp_f32_e32 v11, v11
	s_nop 0
	s_nop 0
	v_rcp_f32_e32 v10, v10
	s_nop 0
	v_pk_mul_f32 v[10:11], v[10:11], v[12:13]
	v_pk_add_f32 v[12:13], v[16:17], 1.0 op_sel_hi:[1,0]
	s_nop 0
	s_nop 0
	v_rcp_f32_e32 v13, v13
	s_nop 0
	s_nop 0
	v_rcp_f32_e32 v12, v12
	s_nop 0
	v_pk_mul_f32 v[12:13], v[12:13], v[14:15]
	v_and_b32_sdwa v14, v11, v225 dst_sel:DWORD dst_unused:UNUSED_PAD src0_sel:WORD_1 src1_sel:DWORD
	v_and_b32_sdwa v15, v10, v225 dst_sel:DWORD dst_unused:UNUSED_PAD src0_sel:WORD_1 src1_sel:DWORD
	v_add3_u32 v10, v10, v15, s23
	v_add3_u32 v11, v11, v14, s23
	v_and_b32_sdwa v14, v13, v225 dst_sel:DWORD dst_unused:UNUSED_PAD src0_sel:WORD_1 src1_sel:DWORD
	v_and_b32_sdwa v15, v12, v225 dst_sel:DWORD dst_unused:UNUSED_PAD src0_sel:WORD_1 src1_sel:DWORD
	v_add3_u32 v13, v13, v14, s23
	v_add3_u32 v12, v12, v15, s23
	v_and_b32_e32 v13, 0xffff0000, v13
	v_and_b32_e32 v12, 0xffff0000, v12
	v_or_b32_sdwa v11, v13, v11 dst_sel:DWORD dst_unused:UNUSED_PAD src0_sel:DWORD src1_sel:WORD_1
	v_or_b32_sdwa v10, v12, v10 dst_sel:DWORD dst_unused:UNUSED_PAD src0_sel:DWORD src1_sel:WORD_1
	v_lshl_add_u64 v[12:13], v[30:31], 0, v[88:89]
	global_store_dwordx2 v[12:13], v[10:11], off
	v_mov_b32_e32 v10, v214
	v_mov_b32_e32 v11, v215
	v_mov_b32_e32 v12, v216
	v_mov_b32_e32 v13, v217
	ds_read_b64 v[14:15], v110
	v_pk_add_f32 v[6:7], v[6:7], v[10:11]
	v_pk_add_f32 v[8:9], v[8:9], v[12:13]
	v_mul_f32_e32 v7, 0xbfb8aa3b, v7
	v_mul_f32_e32 v6, 0xbfb8aa3b, v6
	v_exp_f32_e32 v16, v7
	v_mul_f32_e32 v7, 0xbfb8aa3b, v8
	v_exp_f32_e32 v6, v6
	v_exp_f32_e32 v7, v7
	v_mul_f32_e32 v8, 0xbfb8aa3b, v9
	v_exp_f32_e32 v17, v8
	s_waitcnt lgkmcnt(0)
	v_lshlrev_b32_e32 v9, 16, v15
	v_pk_add_f32 v[6:7], v[6:7], 1.0 op_sel_hi:[1,0]
	v_lshlrev_b32_e32 v8, 16, v14
	v_and_b32_e32 v15, 0xffff0000, v15
	v_and_b32_e32 v14, 0xffff0000, v14
	v_pk_add_f32 v[2:3], v[2:3], v[10:11]
	v_rcp_f32_e32 v7, v7
	s_nop 0
	v_pk_add_f32 v[4:5], v[4:5], v[12:13]
	v_mul_f32_e32 v3, 0xbfb8aa3b, v3
	v_mul_f32_e32 v2, 0xbfb8aa3b, v2
	v_rcp_f32_e32 v6, v6
	s_nop 0
	v_pk_mul_f32 v[6:7], v[6:7], v[8:9]
	v_pk_add_f32 v[8:9], v[16:17], 1.0 op_sel_hi:[1,0]
	v_exp_f32_e32 v2, v2
	s_nop 0
	v_rcp_f32_e32 v9, v9
	s_nop 0
	s_nop 0
	v_rcp_f32_e32 v8, v8
	s_nop 0
	v_pk_mul_f32 v[8:9], v[8:9], v[14:15]
	v_and_b32_sdwa v14, v7, v225 dst_sel:DWORD dst_unused:UNUSED_PAD src0_sel:WORD_1 src1_sel:DWORD
	v_and_b32_sdwa v15, v6, v225 dst_sel:DWORD dst_unused:UNUSED_PAD src0_sel:WORD_1 src1_sel:DWORD
	v_add3_u32 v6, v6, v15, s23
	v_add3_u32 v7, v7, v14, s23
	v_and_b32_sdwa v14, v9, v225 dst_sel:DWORD dst_unused:UNUSED_PAD src0_sel:WORD_1 src1_sel:DWORD
	v_and_b32_sdwa v15, v8, v225 dst_sel:DWORD dst_unused:UNUSED_PAD src0_sel:WORD_1 src1_sel:DWORD
	v_add3_u32 v9, v9, v14, s23
	v_add3_u32 v8, v8, v15, s23
	v_and_b32_e32 v9, 0xffff0000, v9
	v_and_b32_e32 v8, 0xffff0000, v8
	v_or_b32_sdwa v7, v9, v7 dst_sel:DWORD dst_unused:UNUSED_PAD src0_sel:DWORD src1_sel:WORD_1
	v_or_b32_sdwa v6, v8, v6 dst_sel:DWORD dst_unused:UNUSED_PAD src0_sel:DWORD src1_sel:WORD_1
	v_lshl_add_u64 v[8:9], v[34:35], 0, v[90:91]
	global_store_dwordx2 v[8:9], v[6:7], off
	v_exp_f32_e32 v8, v3
	v_mul_f32_e32 v3, 0xbfb8aa3b, v4
	v_exp_f32_e32 v3, v3
	ds_read_b64 v[6:7], v111
	v_mul_f32_e32 v4, 0xbfb8aa3b, v5
	v_exp_f32_e32 v9, v4
	v_pk_add_f32 v[2:3], v[2:3], 1.0 op_sel_hi:[1,0]
	s_waitcnt lgkmcnt(0)
	v_lshlrev_b32_e32 v5, 16, v7
	v_lshlrev_b32_e32 v4, 16, v6
	v_and_b32_e32 v7, 0xffff0000, v7
	v_and_b32_e32 v6, 0xffff0000, v6
	v_rcp_f32_e32 v3, v3
	s_nop 0
	s_nop 0
	v_rcp_f32_e32 v2, v2
	s_nop 0
	v_pk_mul_f32 v[2:3], v[2:3], v[4:5]
	v_pk_add_f32 v[4:5], v[8:9], 1.0 op_sel_hi:[1,0]
	s_nop 0
	s_nop 0
	v_rcp_f32_e32 v5, v5
	s_nop 0
	s_nop 0
	v_rcp_f32_e32 v4, v4
	s_nop 0
	v_pk_mul_f32 v[4:5], v[4:5], v[6:7]
	v_and_b32_sdwa v6, v3, v225 dst_sel:DWORD dst_unused:UNUSED_PAD src0_sel:WORD_1 src1_sel:DWORD
	v_and_b32_sdwa v7, v2, v225 dst_sel:DWORD dst_unused:UNUSED_PAD src0_sel:WORD_1 src1_sel:DWORD
	v_add3_u32 v2, v2, v7, s23
	v_add3_u32 v3, v3, v6, s23
	v_and_b32_sdwa v6, v5, v225 dst_sel:DWORD dst_unused:UNUSED_PAD src0_sel:WORD_1 src1_sel:DWORD
	v_and_b32_sdwa v7, v4, v225 dst_sel:DWORD dst_unused:UNUSED_PAD src0_sel:WORD_1 src1_sel:DWORD
	v_add3_u32 v5, v5, v6, s23
	v_add3_u32 v4, v4, v7, s23
	v_and_b32_e32 v5, 0xffff0000, v5
	v_and_b32_e32 v4, 0xffff0000, v4
	v_or_b32_sdwa v3, v5, v3 dst_sel:DWORD dst_unused:UNUSED_PAD src0_sel:DWORD src1_sel:WORD_1
	v_or_b32_sdwa v2, v4, v2 dst_sel:DWORD dst_unused:UNUSED_PAD src0_sel:DWORD src1_sel:WORD_1
	v_lshl_add_u64 v[4:5], v[30:31], 0, v[90:91]
	global_store_dwordx2 v[4:5], v[2:3], off
	s_waitcnt lgkmcnt(0)
	s_barrier
	s_cbranch_scc0 .LBB0_1195
